# attention loop: all 44 per-tile s_setprio toggles deleted (VALU->MFMA wait states kept via s_nop 1)
# speedup vs baseline: 1.0021x; 1.0021x over previous
; #define LAS __attribute__((address_space(3)))
; #define AT_LDK(buf, grp) do { _Pragma("unroll") for (int q_ = 0; q_ < 2; ++q_) { kf[buf][2 * q_] = *(const LAS bf16x8*)(ka + ((grp) * 2 + q_) * 32); kf[buf][2 * q_ + 1] = *(const LAS bf16x8*)(ka + 32 * AT_KROW + ((grp) * 2 + q_) * 32); } } while (0)
; __device__ __forceinline__ void attn_phase(LAS unsigned char* lds, const bf16* Q, const bf16* KV, const bf16* KPE, const float* rope, bf16* mix, int bid, int G, int tid) {
;     ...
;         for (int kt = 0; kt < ntiles; ++kt) {
;             if (kt + 1 < ntiles) AT_ISSUE(kt + 1);
;             const int key0 = kt * 64;
;             const LAS unsigned char* kb_ = lds + (kt & 1) * AT_BUF; const LAS unsigned char* vb_ = kb_ + AT_KB;
;             if (key0 <= qlo + 31) {
;                 f32x16 S0, S1;
; #pragma unroll
;                 for (int e = 0; e < 16; ++e) { S0[e] = 0.f; S1[e] = 0.f; }
;                 const LAS unsigned char* ka = kb_ + l32 * AT_KROW + hh * 16;
;                 bf16x8 kf[2][4];
;     ...
;                 AT_LDK(0, 0); __builtin_amdgcn_sched_barrier(0);
; #pragma unroll
;                 for (int grp = 0; grp < 6; ++grp) {
;                     if (grp < 5) { AT_LDK((grp + 1) & 1, grp + 1); }
;                     __builtin_amdgcn_sched_barrier(0);
;                     __builtin_amdgcn_s_setprio(1);
; #pragma unroll
;                     for (int q_ = 0; q_ < 2; ++q_) {
;                         S0 = __builtin_amdgcn_mfma_f32_32x32x16_bf16(kf[grp & 1][2 * q_], qf[grp * 2 + q_], S0, 0, 0, 0);
;                         S1 = __builtin_amdgcn_mfma_f32_32x32x16_bf16(kf[grp & 1][2 * q_ + 1], qf[grp * 2 + q_], S1, 0, 0, 0); }
;                     __builtin_amdgcn_s_setprio(0);
;                     __builtin_amdgcn_sched_barrier(0); }
;     ...
;                 const LAS unsigned char* va = vb_ + (4 * hh + ((lane & 15) >> 2)) * AT_VROW + (16 * ((lane >> 4) & 1) + 4 * (lane & 3)) * 2;
;                 s16x4 vf[2][4];
;     ...
;                 AT_LDV(0, 0); __builtin_amdgcn_sched_barrier(0);
;                 if (key0 + 63 > qlo) { const int qq = qlo + l32;
; #pragma unroll
;                     for (int e = 0; e < 16; ++e) { const int key = key0 + 8 * (e >> 2) + 4 * hh + (e & 3);
;                         if (key > qq) S0[e] = -1e30f; if (key + 32 > qq) S1[e] = -1e30f; } }
.LBB0_253:
	s_sub_i32 s5, s0, 63
	s_cmp_gt_i32 s5, s11
	s_cbranch_scc1 .LBB0_259
	s_bitcmp1_b32 s4, 0
	s_cselect_b32 s4, 0xb400, 0
	s_add_i32 s4, s4, 0
	v_add3_u32 v236, s4, v203, v96
	ds_read_b128 v[64:67], v236
	ds_read_b128 v[166:169], v236 offset:32
	ds_read_b128 v[68:71], v236 offset:12800
	ds_read_b128 v[170:173], v236 offset:12832
	ds_read_b128 v[208:211], v236 offset:64
	ds_read_b128 v[212:215], v236 offset:96
	ds_read_b128 v[228:231], v236 offset:12864
	ds_read_b128 v[232:235], v236 offset:12896
	s_waitcnt lgkmcnt(0)
	v_mfma_f32_32x32x16_bf16 v[80:95], v[64:67], v[98:101], 0
	v_mfma_f32_32x32x16_bf16 v[64:79], v[68:71], v[98:101], 0
	v_mfma_f32_32x32x16_bf16 v[80:95], v[166:169], v[102:105], v[80:95]
	v_mfma_f32_32x32x16_bf16 v[64:79], v[170:173], v[102:105], v[64:79]
	ds_read_b128 v[166:169], v236 offset:128
	ds_read_b128 v[170:173], v236 offset:160
	ds_read_b128 v[242:245], v236 offset:12928
	ds_read_b128 v[246:249], v236 offset:12960
	v_mfma_f32_32x32x16_bf16 v[80:95], v[208:211], v[106:109], v[80:95]
	v_mfma_f32_32x32x16_bf16 v[64:79], v[228:231], v[106:109], v[64:79]
	v_mfma_f32_32x32x16_bf16 v[80:95], v[212:215], v[110:113], v[80:95]
	v_mfma_f32_32x32x16_bf16 v[64:79], v[232:235], v[110:113], v[64:79]
	ds_read_b128 v[208:211], v236 offset:192
	ds_read_b128 v[212:215], v236 offset:224
	ds_read_b128 v[228:231], v236 offset:12992
	ds_read_b128 v[232:235], v236 offset:13024
	s_waitcnt lgkmcnt(0)
	v_mfma_f32_32x32x16_bf16 v[80:95], v[166:169], v[114:117], v[80:95]
	v_mfma_f32_32x32x16_bf16 v[64:79], v[242:245], v[114:117], v[64:79]
	v_mfma_f32_32x32x16_bf16 v[80:95], v[170:173], v[118:121], v[80:95]
	v_mfma_f32_32x32x16_bf16 v[64:79], v[246:249], v[118:121], v[64:79]
	ds_read_b128 v[166:169], v236 offset:256
	ds_read_b128 v[170:173], v236 offset:288
	ds_read_b128 v[242:245], v236 offset:13056
	ds_read_b128 v[246:249], v236 offset:13088
	v_mfma_f32_32x32x16_bf16 v[80:95], v[208:211], v[122:125], v[80:95]
	v_mfma_f32_32x32x16_bf16 v[64:79], v[228:231], v[122:125], v[64:79]
	v_mfma_f32_32x32x16_bf16 v[80:95], v[212:215], v[126:129], v[80:95]
	v_mfma_f32_32x32x16_bf16 v[64:79], v[232:235], v[126:129], v[64:79]
	ds_read_b128 v[208:211], v236 offset:320
	ds_read_b128 v[212:215], v236 offset:352
	ds_read_b128 v[228:231], v236 offset:13120
	ds_read_b128 v[232:235], v236 offset:13152
	s_waitcnt lgkmcnt(0)
	v_mfma_f32_32x32x16_bf16 v[80:95], v[166:169], v[130:133], v[80:95]
	v_mfma_f32_32x32x16_bf16 v[64:79], v[242:245], v[130:133], v[64:79]
	v_mfma_f32_32x32x16_bf16 v[80:95], v[170:173], v[158:161], v[80:95]
	v_mfma_f32_32x32x16_bf16 v[64:79], v[246:249], v[158:161], v[64:79]
	v_mfma_f32_32x32x16_bf16 v[80:95], v[208:211], v[134:137], v[80:95]
	v_add_u32_e32 v166, s4, v204
	v_add_u32_e32 v208, v166, v205
	ds_read_b64_tr_b16 v[170:171], v208 offset:25600
	ds_read_b64_tr_b16 v[172:173], v208 offset:28160
	ds_read_b64_tr_b16 v[168:169], v208 offset:28224
	ds_read_b64_tr_b16 v[166:167], v208 offset:25664
	v_mfma_f32_32x32x16_bf16 v[64:79], v[228:231], v[134:137], v[64:79]
	v_mfma_f32_32x32x16_bf16 v[80:95], v[212:215], v[162:165], v[80:95]
	v_mfma_f32_32x32x16_bf16 v[64:79], v[232:235], v[162:165], v[64:79]
	s_cmp_le_i32 s0, s8
	s_cbranch_scc1 .LBB0_256
	v_add_u32_e32 v209, s0, v189
	v_subrev_u32_e32 v211, 31, v209
	v_subrev_u32_e32 v210, 63, v209
	v_cmp_le_i32_e32 vcc, v211, v206
	s_nop 5
	v_cndmask_b32_e32 v64, v224, v64, vcc
	v_cmp_lt_i32_e32 vcc, v210, v206
	s_nop 1
	v_cndmask_b32_e32 v81, v224, v81, vcc
	v_cmp_le_i32_e32 vcc, v210, v206
	v_subrev_u32_e32 v210, 30, v209
	s_nop 0
	v_cndmask_b32_e32 v80, v224, v80, vcc
	v_cmp_le_i32_e32 vcc, v210, v206
	v_subrev_u32_e32 v210, 61, v209
	s_nop 0
	v_cndmask_b32_e32 v65, v224, v65, vcc
	v_cmp_le_i32_e32 vcc, v210, v206
	v_subrev_u32_e32 v210, 29, v209
	s_nop 0
	v_cndmask_b32_e32 v82, v224, v82, vcc
	v_cmp_le_i32_e32 vcc, v210, v206
	v_subrev_u32_e32 v210, 60, v209
	s_nop 0
	v_cndmask_b32_e32 v66, v224, v66, vcc
	v_cmp_le_i32_e32 vcc, v210, v206
	v_subrev_u32_e32 v210, 28, v209
	s_nop 0
	v_cndmask_b32_e32 v83, v224, v83, vcc
	v_cmp_le_i32_e32 vcc, v210, v206
	v_subrev_u32_e32 v210, 55, v209
	s_nop 0
	v_cndmask_b32_e32 v67, v224, v67, vcc
	v_cmp_le_i32_e32 vcc, v210, v206
	v_subrev_u32_e32 v210, 23, v209
	s_nop 0
	v_cndmask_b32_e32 v84, v224, v84, vcc
	v_cmp_le_i32_e32 vcc, v210, v206
	v_subrev_u32_e32 v210, 54, v209
	s_nop 0
	v_cndmask_b32_e32 v68, v224, v68, vcc
	v_cmp_le_i32_e32 vcc, v210, v206
	v_subrev_u32_e32 v210, 22, v209
	s_nop 0
	v_cndmask_b32_e32 v85, v224, v85, vcc
	v_cmp_le_i32_e32 vcc, v210, v206
	v_subrev_u32_e32 v210, 53, v209
	s_nop 0
	v_cndmask_b32_e32 v69, v224, v69, vcc
	v_cmp_le_i32_e32 vcc, v210, v206
	v_subrev_u32_e32 v210, 21, v209
	s_nop 0
	v_cndmask_b32_e32 v86, v224, v86, vcc
	v_cmp_le_i32_e32 vcc, v210, v206
	v_subrev_u32_e32 v210, 52, v209
	s_nop 0
	v_cndmask_b32_e32 v70, v224, v70, vcc
	v_cmp_le_i32_e32 vcc, v210, v206
	v_subrev_u32_e32 v210, 20, v209
	s_nop 0
	v_cndmask_b32_e32 v87, v224, v87, vcc
	v_cmp_le_i32_e32 vcc, v210, v206
	v_subrev_u32_e32 v210, 47, v209
	s_nop 0
	v_cndmask_b32_e32 v71, v224, v71, vcc
	v_cmp_le_i32_e32 vcc, v210, v206
	v_add_u32_e32 v210, -15, v209
	s_nop 0
	v_cndmask_b32_e32 v88, v224, v88, vcc
	v_cmp_le_i32_e32 vcc, v210, v206
	v_subrev_u32_e32 v210, 46, v209
	s_nop 0
	v_cndmask_b32_e32 v72, v224, v72, vcc
	v_cmp_le_i32_e32 vcc, v210, v206
	v_add_u32_e32 v210, -14, v209
	s_nop 0
	v_cndmask_b32_e32 v89, v224, v89, vcc
	v_cmp_le_i32_e32 vcc, v210, v206
	v_subrev_u32_e32 v210, 45, v209
	s_nop 0
	v_cndmask_b32_e32 v73, v224, v73, vcc
	v_cmp_le_i32_e32 vcc, v210, v206
	v_add_u32_e32 v210, -13, v209
	s_nop 0
	v_cndmask_b32_e32 v90, v224, v90, vcc
	v_cmp_le_i32_e32 vcc, v210, v206
	v_subrev_u32_e32 v210, 44, v209
	s_nop 0
	v_cndmask_b32_e32 v74, v224, v74, vcc
	v_cmp_le_i32_e32 vcc, v210, v206
	v_add_u32_e32 v210, -12, v209
	s_nop 0
	v_cndmask_b32_e32 v91, v224, v91, vcc
	v_cmp_le_i32_e32 vcc, v210, v206
	v_subrev_u32_e32 v210, 39, v209
	s_nop 0
	v_cndmask_b32_e32 v75, v224, v75, vcc
	v_cmp_le_i32_e32 vcc, v210, v206
	v_add_u32_e32 v210, -7, v209
	s_nop 0
	v_cndmask_b32_e32 v92, v224, v92, vcc
	v_cmp_le_i32_e32 vcc, v210, v206
	v_subrev_u32_e32 v210, 38, v209
	s_nop 0
	v_cndmask_b32_e32 v76, v224, v76, vcc
	v_cmp_le_i32_e32 vcc, v210, v206
	v_add_u32_e32 v210, -6, v209
	s_nop 0
	v_cndmask_b32_e32 v93, v224, v93, vcc
	v_cmp_le_i32_e32 vcc, v210, v206
	v_subrev_u32_e32 v210, 37, v209
	s_nop 0
	v_cndmask_b32_e32 v77, v224, v77, vcc
	v_cmp_le_i32_e32 vcc, v210, v206
	v_add_u32_e32 v210, -5, v209
	s_nop 0
	v_cndmask_b32_e32 v94, v224, v94, vcc
	v_cmp_le_i32_e32 vcc, v210, v206
	v_subrev_u32_e32 v210, 36, v209
	v_add_u32_e32 v209, -4, v209
	v_cndmask_b32_e32 v78, v224, v78, vcc
	v_cmp_le_i32_e32 vcc, v210, v206
	s_nop 1
	v_cndmask_b32_e32 v95, v224, v95, vcc
	v_cmp_le_i32_e32 vcc, v209, v206
	s_nop 1
	v_cndmask_b32_e32 v79, v224, v79, vcc

; __device__ __forceinline__ u32x4 pack8(const float (&f)[8]) { u32x4 w; w.x = pk_bf16(f[0], f[1]); w.y = pk_bf16(f[2], f[3]); w.z = pk_bf16(f[4], f[5]); w.w = pk_bf16(f[6], f[7]); return w; }
; #define AT_LDV(buf, hs) do { const LAS unsigned char* vp_ = va + ((((hs) >> 1) >> 1) * 32 + 16 * (((hs) >> 1) & 1)) * AT_VROW + ((hs) & 1) * 128; _Pragma("unroll") for (int d_ = 0; d_ < 2; ++d_) { vf[buf][2 * d_] = vtr(vp_ + d_ * 64); vf[buf][2 * d_ + 1] = vtr(vp_ + 8 * AT_VROW + d_ * 64); } } while (0)
; __device__ __forceinline__ void attn_phase(LAS unsigned char* lds, const bf16* Q, const bf16* KV, const bf16* KPE, const float* rope, bf16* mix, int bid, int G, int tid) {
;     ...
;                 float rs = 0.f;
; #pragma unroll
;                 for (int e = 0; e < 16; ++e) { S0[e] = __builtin_amdgcn_exp2f(S0[e] - mnew); S1[e] = __builtin_amdgcn_exp2f(S1[e] - mnew); rs += S0[e] + S1[e]; }
;                 lrun = lrun * alpha + rs;
;                 if (__builtin_amdgcn_ballot_w64(alpha != 1.0f) != 0ull) {
; #pragma unroll
;                     for (int i = 0; i < 4; ++i)
; #pragma unroll
;                         for (int e = 0; e < 16; ++e) O[i][e] *= alpha; }
; #pragma unroll
;                 for (int hs = 0; hs < 8; ++hs) { const int st = hs >> 1;
;                     if (hs < 7) { AT_LDV((hs + 1) & 1, hs + 1); }
;                     __builtin_amdgcn_sched_barrier(0);
;                     float pf[8];
; #pragma unroll
;                     for (int e = 0; e < 8; ++e) pf[e] = (st >> 1) ? S1[8 * (st & 1) + e] : S0[8 * (st & 1) + e];
;                     const bf16x8 pb = __builtin_bit_cast(bf16x8, pack8(pf));
; #pragma unroll
;                     for (int d_ = 0; d_ < 2; ++d_) { const int dvt = (hs & 1) * 2 + d_; const s16x4 lo = vf[hs & 1][2 * d_], hi = vf[hs & 1][2 * d_ + 1];
;                         const bf16x8 A = (bf16x8){lo[0], lo[1], lo[2], lo[3], hi[0], hi[1], hi[2], hi[3]};
;                         __builtin_amdgcn_s_setprio(1); O[dvt] = __builtin_amdgcn_mfma_f32_32x32x16_bf16(A, pb, O[dvt], 0, 0, 0); __builtin_amdgcn_s_setprio(0); }
;                     __builtin_amdgcn_sched_barrier(0); }
.LBB0_258:
	v_sub_f32_e32 v80, v80, v209
	v_sub_f32_e32 v64, v64, v209
	v_exp_f32_e32 v80, v80
	v_exp_f32_e32 v210, v64
	v_sub_f32_e32 v81, v81, v209
	v_sub_f32_e32 v65, v65, v209
	v_exp_f32_e32 v81, v81
	v_exp_f32_e32 v211, v65
	v_add_f32_e32 v64, v80, v210
	v_add_f32_e32 v64, 0, v64
	v_add_f32_e32 v65, v81, v211
	v_add_f32_e32 v64, v65, v64
	v_sub_f32_e32 v65, v82, v209
	v_exp_f32_e32 v82, v65
	v_sub_f32_e32 v65, v66, v209
	v_exp_f32_e32 v212, v65
	s_nop 0
	v_add_f32_e32 v65, v82, v212
	v_add_f32_e32 v64, v65, v64
	v_sub_f32_e32 v65, v83, v209
	v_exp_f32_e32 v83, v65
	v_sub_f32_e32 v65, v67, v209
	v_exp_f32_e32 v213, v65
	s_nop 0
	v_add_f32_e32 v65, v83, v213
	v_add_f32_e32 v64, v65, v64
	v_sub_f32_e32 v65, v84, v209
	v_exp_f32_e32 v84, v65
	v_sub_f32_e32 v65, v68, v209
	v_exp_f32_e32 v214, v65
	s_nop 0
	v_add_f32_e32 v65, v84, v214
	v_add_f32_e32 v64, v65, v64
	v_sub_f32_e32 v65, v85, v209
	v_exp_f32_e32 v85, v65
	v_sub_f32_e32 v65, v69, v209
	v_exp_f32_e32 v215, v65
	s_nop 0
	v_add_f32_e32 v65, v85, v215
	v_add_f32_e32 v64, v65, v64
	v_sub_f32_e32 v65, v86, v209
	v_exp_f32_e32 v86, v65
	v_sub_f32_e32 v65, v70, v209
	v_exp_f32_e32 v228, v65
	s_nop 0
	v_add_f32_e32 v65, v86, v228
	v_add_f32_e32 v64, v65, v64
	v_sub_f32_e32 v65, v87, v209
	v_exp_f32_e32 v87, v65
	v_sub_f32_e32 v65, v71, v209
	v_exp_f32_e32 v229, v65
	s_nop 0
	v_add_f32_e32 v65, v87, v229
	v_add_f32_e32 v64, v65, v64
	v_sub_f32_e32 v65, v88, v209
	v_exp_f32_e32 v88, v65
	v_sub_f32_e32 v65, v72, v209
	v_exp_f32_e32 v230, v65
	s_nop 0
	v_add_f32_e32 v65, v88, v230
	v_add_f32_e32 v64, v65, v64
	v_sub_f32_e32 v65, v89, v209
	v_exp_f32_e32 v89, v65
	v_sub_f32_e32 v65, v73, v209
	v_exp_f32_e32 v231, v65
	s_nop 0
	v_add_f32_e32 v65, v89, v231
	v_add_f32_e32 v64, v65, v64
	v_sub_f32_e32 v65, v90, v209
	v_exp_f32_e32 v90, v65
	v_sub_f32_e32 v65, v74, v209
	v_exp_f32_e32 v232, v65
	s_nop 0
	v_add_f32_e32 v65, v90, v232
	v_add_f32_e32 v64, v65, v64
	v_sub_f32_e32 v65, v91, v209
	v_exp_f32_e32 v91, v65
	v_sub_f32_e32 v65, v75, v209
	v_exp_f32_e32 v233, v65
	s_nop 0
	v_add_f32_e32 v65, v91, v233
	v_add_f32_e32 v64, v65, v64
	v_sub_f32_e32 v65, v92, v209
	v_exp_f32_e32 v92, v65
	v_sub_f32_e32 v65, v76, v209
	v_exp_f32_e32 v234, v65
	s_nop 0
	v_add_f32_e32 v65, v92, v234
	v_add_f32_e32 v64, v65, v64
	v_sub_f32_e32 v65, v93, v209
	v_exp_f32_e32 v93, v65
	v_sub_f32_e32 v65, v77, v209
	v_exp_f32_e32 v235, v65
	s_nop 0
	v_add_f32_e32 v65, v93, v235
	v_add_f32_e32 v64, v65, v64
	v_sub_f32_e32 v65, v94, v209
	v_exp_f32_e32 v94, v65
	v_sub_f32_e32 v65, v78, v209
	v_exp_f32_e32 v236, v65
	s_nop 0
	v_add_f32_e32 v65, v94, v236
	v_add_f32_e32 v64, v65, v64
	v_sub_f32_e32 v65, v95, v209
	v_exp_f32_e32 v95, v65
	v_sub_f32_e32 v65, v79, v209
	v_exp_f32_e32 v237, v65
	s_nop 0
	v_add_f32_e32 v65, v95, v237
	v_add_f32_e32 v242, v65, v64
	ds_read_b64_tr_b16 v[64:65], v208 offset:25728
	ds_read_b64_tr_b16 v[66:67], v208 offset:28288
	ds_read_b64_tr_b16 v[68:69], v208 offset:25792
	ds_read_b64_tr_b16 v[70:71], v208 offset:28352
	v_fmac_f32_e32 v242, v207, v184
	v_cvt_pk_bf16_f32 v72, v80, v81
	v_cvt_pk_bf16_f32 v73, v82, v83
	v_cvt_pk_bf16_f32 v74, v84, v85
	v_cvt_pk_bf16_f32 v75, v86, v87
	s_nop 1
	v_mfma_f32_32x32x16_bf16 v[48:63], v[170:173], v[72:75], v[48:63]
	v_mfma_f32_32x32x16_bf16 v[32:47], v[166:169], v[72:75], v[32:47]
	ds_read_b64_tr_b16 v[76:77], v208 offset:30720
	ds_read_b64_tr_b16 v[78:79], v208 offset:33280
	ds_read_b64_tr_b16 v[80:81], v208 offset:30784
	ds_read_b64_tr_b16 v[82:83], v208 offset:33344
	s_waitcnt lgkmcnt(0)
	v_mfma_f32_32x32x16_bf16 v[16:31], v[64:67], v[72:75], v[16:31]
	v_mfma_f32_32x32x16_bf16 v[0:15], v[68:71], v[72:75], v[0:15]
	ds_read_b64_tr_b16 v[64:65], v208 offset:30848
	ds_read_b64_tr_b16 v[66:67], v208 offset:33408
	ds_read_b64_tr_b16 v[68:69], v208 offset:30912
	ds_read_b64_tr_b16 v[70:71], v208 offset:33472
	v_cvt_pk_bf16_f32 v72, v88, v89
	v_cvt_pk_bf16_f32 v73, v90, v91
	v_cvt_pk_bf16_f32 v74, v92, v93
	v_cvt_pk_bf16_f32 v75, v94, v95
	s_nop 1
	v_mfma_f32_32x32x16_bf16 v[48:63], v[76:79], v[72:75], v[48:63]
	v_mfma_f32_32x32x16_bf16 v[32:47], v[80:83], v[72:75], v[32:47]
	ds_read_b64_tr_b16 v[76:77], v208 offset:35840
	ds_read_b64_tr_b16 v[78:79], v208 offset:38400
	ds_read_b64_tr_b16 v[82:83], v208 offset:38464
	ds_read_b64_tr_b16 v[80:81], v208 offset:35904
	s_waitcnt lgkmcnt(0)
	v_mfma_f32_32x32x16_bf16 v[16:31], v[64:67], v[72:75], v[16:31]
	v_mfma_f32_32x32x16_bf16 v[0:15], v[68:71], v[72:75], v[0:15]
	ds_read_b64_tr_b16 v[64:65], v208 offset:35968
	ds_read_b64_tr_b16 v[66:67], v208 offset:38528
	ds_read_b64_tr_b16 v[70:71], v208 offset:38592
	ds_read_b64_tr_b16 v[68:69], v208 offset:36032
	v_cvt_pk_bf16_f32 v72, v210, v211
	v_cvt_pk_bf16_f32 v73, v212, v213
	v_cvt_pk_bf16_f32 v74, v214, v215
	v_cvt_pk_bf16_f32 v75, v228, v229
	s_nop 1
	v_mfma_f32_32x32x16_bf16 v[48:63], v[76:79], v[72:75], v[48:63]
	v_mfma_f32_32x32x16_bf16 v[32:47], v[80:83], v[72:75], v[32:47]
	ds_read_b64_tr_b16 v[76:77], v208 offset:40960
	ds_read_b64_tr_b16 v[78:79], v208 offset:43520
	ds_read_b64_tr_b16 v[82:83], v208 offset:43584
	ds_read_b64_tr_b16 v[80:81], v208 offset:41024
	s_waitcnt lgkmcnt(0)
	v_mfma_f32_32x32x16_bf16 v[16:31], v[64:67], v[72:75], v[16:31]
	v_mfma_f32_32x32x16_bf16 v[0:15], v[68:71], v[72:75], v[0:15]
	ds_read_b64_tr_b16 v[64:65], v208 offset:41088
	ds_read_b64_tr_b16 v[66:67], v208 offset:43648
	ds_read_b64_tr_b16 v[70:71], v208 offset:43712
	ds_read_b64_tr_b16 v[68:69], v208 offset:41152
	v_cvt_pk_bf16_f32 v72, v230, v231
	v_cvt_pk_bf16_f32 v73, v232, v233
	v_cvt_pk_bf16_f32 v74, v234, v235
	v_cvt_pk_bf16_f32 v75, v236, v237
	s_nop 1
	v_mfma_f32_32x32x16_bf16 v[48:63], v[76:79], v[72:75], v[48:63]
	v_mfma_f32_32x32x16_bf16 v[32:47], v[80:83], v[72:75], v[32:47]
	s_waitcnt lgkmcnt(0)
	v_mfma_f32_32x32x16_bf16 v[16:31], v[64:67], v[72:75], v[16:31]
	v_mfma_f32_32x32x16_bf16 v[0:15], v[68:71], v[72:75], v[0:15]
	v_mov_b32_e32 v207, v242
	s_andn2_b64 vcc, exec, s[34:35]
	s_cbranch_vccz .LBB0_260
	s_branch .LBB0_261
